# mixers queue order: sample-attn tickets interleaved 1:2 among the rglru prompt tiles (spreads the nt cache-copy traffic), pool first, rowsum last
# speedup vs baseline: 1.0036x; 1.0036x over previous
.Lq_remap:
	s_cmpk_lt_i32 s81, 0x186
	s_cbranch_scc1 .Lq_old
	s_cmpk_lt_i32 s81, 0x306
	s_cbranch_scc0 .Lq_old
	s_sub_i32 s4, s81, 0x186
	s_mul_hi_u32 s10, s4, 0xaaaaaaab
	s_lshr_b32 s10, s10, 1
	s_mul_i32 s11, s10, 3
	s_sub_i32 s11, s4, s11
	s_lshl_b32 s12, s10, 1
	s_add_i32 s12, s12, s11
	s_addk_i32 s12, 0x102
	s_add_i32 s13, s10, 0x286
	s_cmp_eq_u32 s11, 2
	s_cselect_b32 s81, s13, s12
	s_branch .Lq_go

.Lq_go:
.LBB0_545:
	s_cmpk_gt_i32 s81, 0xff
	s_cbranch_scc0 .LBB0_549
	s_add_i32 s4, s81, 0xffffff00
	s_cmpk_gt_u32 s4, 0x101
	s_cbranch_scc0 .LBB0_578
